# P3: window element, first ret_sample item's q/k/v/gate loads and attn_sample's 11 input loads all issued at phase start (one shared round trip with ret_scan)
# baseline (speedup 1.0000x reference)
; DEV float bf2f(unsigned h) { return __uint_as_float(h << 16); }
; DEV void ret_sample_item(const Params& p, int l, int item, unsigned char* smem) {
;     ...
;   {
;     const int i = tid >> 6, d = tid & 63;
;     qs[tid] = bf2f(Z[(rowbase + i) * NIN + RQ + h * 64 + d]);
;     ks[tid] = bf2f(Z[(rowbase + i) * NIN + RK + h * 64 + d]) * 0.125f;
; #pragma unroll
;     for (int it = 0; it < 2; ++it) { const int idx = tid + it * 512, ii = idx >> 7, e = idx & 127; vs[idx] = bf2f(Z[(rowbase + ii) * NIN + RV + h * 128 + e]); }
; DEV void attn_sample_item(const Params& p, int l, int item, unsigned char* smem) {
;     ...
;   {
;     f32x4 kq[4], vq[4];
; #pragma unroll
;     for (int it = 0; it < 4; ++it) {
;       const int idx4 = tid + it * 512, j = idx4 >> 4, d4 = (idx4 & 15) * 4;
;       kq[it] = *(const f32x4*)(ck + (j * 2 + kvh) * 64 + d4);
;       vq[it] = *(const f32x4*)(cv + (j * 2 + kvh) * 64 + d4);
;     }
;     const int jn = tid >> 6, dn = tid & 63;
;     const bf16_t knb = Z[(rowbase + jn) * NIN + AK + kvh * 64 + dn], vnb = Z[(rowbase + jn) * NIN + AV + kvh * 64 + dn];
;     u32x4 qv = (u32x4){0u, 0u, 0u, 0u};
;     if (tid < 256) { const int r = tid >> 3, kc = tid & 7; qv = *(const u32x4*)(Z + (rowbase + (r & 7)) * NIN + AQ + (kvh * 4 + (r >> 3)) * 64 + kc * 8); }
.LBB0_329:
	s_andn2_b64 vcc, exec, s[0:1]
	s_cbranch_vccnz .LBB0_422
	v_lshl_add_u32 v240, s74, 9, v171
	v_bfe_u32 v241, v240, 7, 7
	v_bfe_u32 v242, v240, 14, 2
	v_cmp_gt_u32_e32 vcc, 0x10000, v240
	v_lshl_or_b32 v241, v242, 12, v241
	v_mov_b32_e32 v243, 0
	v_cndmask_b32_e32 v242, v210, v211, vcc
	v_mul_u32_u24_e32 v241, 0x1b00, v241
	v_lshl_add_u64 v[244:245], s[30:31], 0, v[242:243]
	v_lshlrev_b32_e32 v242, 1, v241
	v_lshl_add_u64 v[244:245], v[244:245], 0, v[242:243]
	v_and_b32_e32 v242, 0x7f, v171
	v_lshlrev_b32_e32 v242, 1, v242
	v_lshl_add_u64 v[244:245], v[244:245], 0, v[242:243]
	v_mov_b32_e32 v242, 0x3450000
	v_lshl_add_u64 v[244:245], v[244:245], 0, v[242:243]
	global_load_ushort v246, v[244:245], off
	s_and_b32 s45, s74, 3
	s_lshl_b32 s44, s74, 1
	s_and_b32 s44, s44, -8
	s_add_u32 s44, s44, 0x4000
	s_lshl_b32 s52, s45, 7
	s_mov_b32 s53, 0
	v_ashrrev_i32_e32 v234, 6, v171
	v_add_u32_e32 v234, s44, v234
	v_mov_b64_e32 v[236:237], s[30:31]
	v_mov_b32_e32 v239, 0
	v_and_b32_e32 v235, 63, v171
	v_mad_u64_u32 v[236:237], vcc, v234, s95, v[236:237]
	v_lshlrev_b32_e32 v238, 1, v235
	v_lshl_add_u64 v[236:237], v[236:237], 0, s[52:53]
	v_lshl_add_u64 v[236:237], v[236:237], 0, v[238:239]
	global_load_ushort v240, v[236:237], off
	global_load_ushort v241, v[236:237], off offset:512
	v_lshl_add_u64 v[236:237], v[236:237], 0, s[52:53]
	global_load_ushort v244, v[236:237], off offset:2048
	global_load_ushort v245, v[236:237], off offset:2176
	v_ashrrev_i32_e32 v234, 7, v171
	v_add_u32_e32 v235, 0x200, v171
	v_add_u32_e32 v234, s44, v234
	v_ashrrev_i32_e32 v235, 7, v235
	v_mov_b64_e32 v[236:237], s[30:31]
	v_add_u32_e32 v235, s44, v235
	v_mad_u64_u32 v[236:237], vcc, v234, s95, v[236:237]
	v_mov_b64_e32 v[238:239], s[30:31]
	s_lshl_b32 s52, s45, 8
	v_mad_u64_u32 v[238:239], vcc, v235, s95, v[238:239]
	v_and_b32_e32 v234, 0x7f, v171
	v_lshlrev_b32_e32 v234, 1, v234
	v_mov_b32_e32 v235, 0
	v_lshl_add_u64 v[236:237], v[236:237], 0, s[52:53]
	v_lshl_add_u64 v[238:239], v[238:239], 0, s[52:53]
	v_lshl_add_u64 v[236:237], v[236:237], 0, v[234:235]
	v_lshl_add_u64 v[238:239], v[238:239], 0, v[234:235]
	global_load_ushort v242, v[236:237], off offset:1024
	global_load_ushort v243, v[238:239], off offset:1024
	v_readlane_b32 s46, v248, 43
	s_lshr_b32 s44, s74, 1
	s_and_b32 s47, s74, 1
	v_readlane_b32 s54, v248, 30
	s_lshl_b32 s46, s46, 7
	s_add_i32 s52, s44, s46
	v_readlane_b32 s55, v248, 31
	s_mov_b32 s53, 0
	s_lshl_b32 s44, s44, 3
	v_readlane_b32 s56, v248, 32
	s_add_i32 s44, s44, 0x4000
	s_lshl_b64 s[52:53], s[52:53], 16
	v_readlane_b32 s57, v248, 33
	v_lshlrev_b32_e32 v148, 2, v171
	v_and_b32_e32 v148, 60, v148
	v_lshlrev_b32_e32 v148, 2, v148
	s_add_u32 s54, s54, s52
	s_addc_u32 s55, s55, s53
	s_add_u32 s56, s56, s52
	s_addc_u32 s57, s57, s53
	v_lshrrev_b32_e32 v149, 3, v171
	v_and_b32_e32 v149, 0x3fffffe, v149
	v_or_b32_e32 v149, s47, v149
	v_lshl_add_u32 v149, v149, 8, v148
	global_load_dwordx4 v[110:113], v149, s[54:55]
	global_load_dwordx4 v[114:117], v149, s[56:57]
	v_add_u32_e32 v149, 0x200, v171
	v_lshrrev_b32_e32 v149, 3, v149
	v_and_b32_e32 v149, 0x3fffffe, v149
	v_or_b32_e32 v149, s47, v149
	v_lshl_add_u32 v149, v149, 8, v148
	global_load_dwordx4 v[118:121], v149, s[54:55]
	global_load_dwordx4 v[122:125], v149, s[56:57]
	v_add_u32_e32 v149, 0x400, v171
	v_lshrrev_b32_e32 v149, 3, v149
	v_and_b32_e32 v149, 0x3fffffe, v149
	v_or_b32_e32 v149, s47, v149
	v_lshl_add_u32 v149, v149, 8, v148
	global_load_dwordx4 v[126:129], v149, s[54:55]
	global_load_dwordx4 v[130:133], v149, s[56:57]
	v_add_u32_e32 v149, 0x600, v171
	v_lshrrev_b32_e32 v149, 3, v149
	v_and_b32_e32 v149, 0x3fffffe, v149
	v_or_b32_e32 v149, s47, v149
	v_lshl_add_u32 v149, v149, 8, v148
	global_load_dwordx4 v[134:137], v149, s[54:55]
	global_load_dwordx4 v[138:141], v149, s[56:57]
	v_ashrrev_i32_e32 v150, 6, v171
	v_add_u32_e32 v150, s44, v150
	v_mul_lo_u32 v150, v150, s95
	v_and_b32_e32 v149, 63, v171
	s_lshl_b32 s52, s47, 7
	v_lshl_add_u32 v150, v149, 1, v150
	s_addk_i32 s52, 0x1000
	v_add_u32_e32 v150, s52, v150
	global_load_ushort v142, v150, s[30:31]
	global_load_ushort v143, v150, s[30:31] offset:256
	v_lshrrev_b32_e32 v151, 3, v171
	v_and_b32_e32 v151, 7, v151
	v_add_u32_e32 v151, s44, v151
	v_mul_lo_u32 v151, v151, s95
	v_and_b32_e32 v149, 0xc0, v171
	v_lshl_add_u32 v149, s47, 8, v149
	v_lshl_add_u32 v151, v149, 1, v151
	v_lshlrev_b32_e32 v149, 4, v171
	v_and_b32_e32 v149, 0x70, v149
	v_add_u32_e32 v151, v151, v149
	global_load_dwordx4 v[144:147], v151, s[30:31] offset:3072
	v_readlane_b32 s45, v248, 43
	s_and_b32 s44, s74, -4
	s_nop 0
	s_lshl_b32 s45, s45, 9
	s_add_i32 s44, s44, s45
	s_and_b32 s45, s74, 3
	s_or_b32 s44, s44, s45
	v_readlane_b32 s52, v248, 28
	v_readlane_b32 s53, v248, 29
	s_ashr_i32 s45, s44, 31
	s_lshl_b64 s[44:45], s[44:45], 15
	v_ashrrev_i32_e32 v236, 7, v171
	v_and_b32_e32 v237, 0x7f, v171
	v_lshl_or_b32 v236, v236, 11, v237
	v_ashrrev_i32_e32 v237, 31, v236
	v_lshlrev_b64 v[236:237], 2, v[236:237]
	s_add_u32 s44, s52, s44
	s_addc_u32 s45, s53, s45
	v_lshl_add_u64 v[234:235], s[44:45], 0, v[236:237]
	s_add_u32 s44, s44, 0x1000
	s_addc_u32 s45, s45, 0
	v_lshl_add_u64 v[238:239], s[44:45], 0, v[236:237]
	global_load_dword v218, v[234:235], off
	global_load_dword v219, v[234:235], off offset:512
	global_load_dword v220, v[234:235], off offset:1024
	global_load_dword v221, v[234:235], off offset:1536
	global_load_dword v222, v[234:235], off offset:2048
	global_load_dword v223, v[234:235], off offset:2560
	global_load_dword v224, v[234:235], off offset:3072
	global_load_dword v225, v[234:235], off offset:3584
	global_load_dword v226, v[238:239], off
	global_load_dword v227, v[238:239], off offset:512
	global_load_dword v228, v[238:239], off offset:1024
	global_load_dword v229, v[238:239], off offset:1536
	global_load_dword v230, v[238:239], off offset:2048
	global_load_dword v231, v[238:239], off offset:2560
	global_load_dword v232, v[238:239], off offset:3072
	global_load_dword v233, v[238:239], off offset:3584
	s_mov_b32 s4, s74
	v_mov_b32_e32 v0, v171
	s_mov_b32 s13, 0x20000
	v_lshl_add_u32 v4, s4, 9, v0
	v_cmp_gt_i32_e32 vcc, s13, v4
	s_and_saveexec_b64 s[0:1], vcc
	v_readlane_b32 s9, v249, 34
	v_readlane_b32 s12, v249, 59
	s_mov_b32 s14, 0x10000
	s_mov_b32 s15, 0xc2fc0000
	s_mov_b32 s16, 0x3f2aaaab
	s_mov_b32 s17, 0x3f317218
	s_mov_b32 s18, 0x33800000
	s_mov_b32 s19, 0x40000
	s_mov_b32 s20, 0x48000
	s_mov_b32 s21, 0x50000
	s_mov_b32 s26, 0x58000
	s_mov_b32 s35, 0x88000
	s_mov_b32 s40, 0x1ffff
	s_cbranch_execz .LBB0_333
	s_add_u32 s2, s28, 0x3500000
	v_readlane_b32 s36, v248, 43
	v_lshlrev_b32_e32 v0, 7, v0
	s_addc_u32 s3, s29, 0
	s_lshl_b32 s6, s36, 4
	v_lshl_add_u32 v5, s4, 16, v0
	s_mov_b64 s[4:5], 0
	v_readlane_b32 s37, v248, 44

; DEV bf16_t f2bf(float f) { return (bf16_t)(cvt_pk_bf16(f, 0.f) & 0xffffu); }
; DEV float bf2f(unsigned h) { return __uint_as_float(h << 16); }
; DEV float sigmoidf_(float x) { return 1.0f / (1.0f + __expf(-x)); }
; DEV void ret_sample_item(const Params& p, int l, int item, unsigned char* smem) {
;     ...
;     const int i = w;
;     const float qd = __expf(lg * (float)(i + 1));
;     float o[2]; float ss = 0.f;
; #pragma unroll
;     for (int c = 0; c < 2; ++c) {
;       const int e = lane + c * 64;
;       float a = qd * (part[(0 * 8 + i) * 128 + e] + part[(1 * 8 + i) * 128 + e] + part[(2 * 8 + i) * 128 + e] + part[(3 * 8 + i) * 128 + e]);
;       for (int j = 0; j <= i; ++j) a += inn[i * 8 + j] * vs[j * 128 + e];
;       o[c] = a; ss += a * a;
;     }
;     ss = wave_sum(ss);
;     const float rstd = rsqrtf(ss * (1.0f / 128.0f) + 1e-6f);
; #pragma unroll
;     for (int c = 0; c < 2; ++c) {
;       bf16_t* zp = Z + (rowbase + i) * NIN + RG + h * 128 + lane + c * 64;
;       const float g = bf2f(*zp);
;       *zp = f2bf(g * sigmoidf_(g) * o[c] * rstd);
;     }
.LBB0_335:
	s_or_b64 exec, exec, s[0:1]
	v_pk_mul_f32 v[2:3], v[0:1], v[0:1]
	v_xor_b32_e32 v4, 32, v202
	v_add_f32_e32 v2, v2, v3
	v_and_b32_e32 v3, 64, v202
	v_add_u32_e32 v3, 64, v3
	v_cmp_lt_i32_e32 vcc, v4, v3
	s_mov_b32 s0, 0x800000
	s_lshl_b32 s6, s6, 1
	v_lshl_add_u64 v[106:107], v[64:65], 0, s[6:7]
	v_lshl_add_u64 v[106:107], v[106:107], 0, v[168:169]
	s_cmp_eq_u32 s12, s74
	s_cbranch_scc1 .Lrs_g1
	global_load_ushort v108, v[106:107], off offset:2048
	global_load_ushort v109, v[106:107], off offset:2176
	s_branch .Lrs_g1d
.Lrs_g1:
	v_mov_b32_e32 v108, v244
	v_mov_b32_e32 v109, v245
.Lrs_g1d:
	v_cndmask_b32_e32 v4, v202, v4, vcc
	v_lshlrev_b32_e32 v4, 2, v4
	ds_bpermute_b32 v4, v4, v2
	s_waitcnt lgkmcnt(0)
	v_add_f32_e32 v2, v2, v4
	v_xor_b32_e32 v4, 16, v202
	v_cmp_lt_i32_e32 vcc, v4, v3
	s_nop 1
	v_cndmask_b32_e32 v4, v202, v4, vcc
	v_lshlrev_b32_e32 v4, 2, v4
	ds_bpermute_b32 v4, v4, v2
	s_waitcnt lgkmcnt(0)
	v_add_f32_e32 v2, v2, v4
	v_xor_b32_e32 v4, 8, v202
	v_cmp_lt_i32_e32 vcc, v4, v3
	s_nop 1
	v_cndmask_b32_e32 v4, v202, v4, vcc
	v_lshlrev_b32_e32 v4, 2, v4
	ds_bpermute_b32 v4, v4, v2
	s_waitcnt lgkmcnt(0)
	v_add_f32_e32 v2, v2, v4
	v_xor_b32_e32 v4, 4, v202
	v_cmp_lt_i32_e32 vcc, v4, v3
	s_nop 1
	v_cndmask_b32_e32 v4, v202, v4, vcc
	v_lshlrev_b32_e32 v4, 2, v4
	ds_bpermute_b32 v4, v4, v2
	s_waitcnt lgkmcnt(0)
	v_add_f32_e32 v2, v2, v4
	v_xor_b32_e32 v4, 2, v202
	v_cmp_lt_i32_e32 vcc, v4, v3
	s_nop 1
	v_cndmask_b32_e32 v4, v202, v4, vcc
	v_lshlrev_b32_e32 v4, 2, v4
	ds_bpermute_b32 v4, v4, v2
	s_waitcnt lgkmcnt(0)
	v_add_f32_e32 v2, v2, v4
	v_xor_b32_e32 v4, 1, v202
	v_cmp_lt_i32_e32 vcc, v4, v3
	s_nop 1
	v_cndmask_b32_e32 v3, v202, v4, vcc
	v_lshlrev_b32_e32 v3, 2, v3
	ds_bpermute_b32 v3, v3, v2
	s_waitcnt lgkmcnt(0)
	v_add_f32_e32 v2, v2, v3
	v_fmamk_f32 v2, v2, 0x3c000000, v170
	v_cmp_gt_f32_e32 vcc, s0, v2
	v_mul_f32_e32 v3, 0x4b800000, v2
	s_nop 0
	v_cndmask_b32_e32 v2, v2, v3, vcc
	v_rsq_f32_e32 v2, v2
	s_nop 0
	v_mul_f32_e32 v3, 0x45800000, v2
	v_cndmask_b32_e32 v4, v2, v3, vcc
	s_waitcnt vmcnt(1)
	v_lshlrev_b32_e32 v5, 16, v108
	v_mul_f32_e32 v6, 0xbfb8aa3b, v5
	v_exp_f32_e32 v6, v6
	s_nop 0
	v_add_f32_e32 v6, 1.0, v6
	v_rcp_f32_e32 v8, v6
	s_nop 0
	v_fma_f32 v9, -v6, v8, 1.0
	v_fmac_f32_e32 v8, v9, v8
	v_mov_b32_e32 v6, v8
	v_mul_f32_e32 v5, v6, v5
	v_mul_f32_e32 v0, v0, v5
	v_mul_f32_e32 v0, v4, v0
	v_cvt_pk_bf16_f32 v0, v0, s0
	global_store_short v[106:107], v0, off offset:2048
	s_waitcnt vmcnt(1)
	v_lshlrev_b32_e32 v0, 16, v109
	v_mul_f32_e32 v5, 0xbfb8aa3b, v0
	v_exp_f32_e32 v5, v5
	s_nop 0
	v_add_f32_e32 v5, 1.0, v5
	v_rcp_f32_e32 v7, v5
	s_nop 0
	v_fma_f32 v8, -v5, v7, 1.0
	v_fmac_f32_e32 v7, v8, v7
	v_mov_b32_e32 v5, v7
	v_mul_f32_e32 v0, v5, v0
	v_mul_f32_e32 v0, v1, v0
	v_mul_f32_e32 v0, v4, v0
	v_cvt_pk_bf16_f32 v0, v0, s0
	global_store_short v[106:107], v0, off offset:2176
	s_barrier

; DEV unsigned cvt_pk_bf16(float lo, float hi) { const f32x2_ v = {lo, hi}; return __builtin_bit_cast(unsigned, __builtin_convertvector(v, bf16x2n_)); }
; DEV bf16_t f2bf(float f) { return (bf16_t)(cvt_pk_bf16(f, 0.f) & 0xffffu); }
; DEV float bf2f(unsigned h) { return __uint_as_float(h << 16); }
; DEV void attn_sample_item(const Params& p, int l, int item, unsigned char* smem) {
;     ...
;   {
;     f32x4 kq[4], vq[4];
; #pragma unroll
;     for (int it = 0; it < 4; ++it) {
;       const int idx4 = tid + it * 512, j = idx4 >> 4, d4 = (idx4 & 15) * 4;
;       kq[it] = *(const f32x4*)(ck + (j * 2 + kvh) * 64 + d4);
;       vq[it] = *(const f32x4*)(cv + (j * 2 + kvh) * 64 + d4);
;     }
;     const int jn = tid >> 6, dn = tid & 63;
;     const bf16_t knb = Z[(rowbase + jn) * NIN + AK + kvh * 64 + dn], vnb = Z[(rowbase + jn) * NIN + AV + kvh * 64 + dn];
;     u32x4 qv = (u32x4){0u, 0u, 0u, 0u};
;     if (tid < 256) { const int r = tid >> 3, kc = tid & 7; qv = *(const u32x4*)(Z + (rowbase + (r & 7)) * NIN + AQ + (kvh * 4 + (r >> 3)) * 64 + kc * 8); }
; #pragma unroll
;     for (int it = 0; it < 4; ++it) {
;       const int idx4 = tid + it * 512, j = idx4 >> 4, d4 = (idx4 & 15) * 4;
;       u32x2 kw; kw.x = cvt_pk_bf16(kq[it][0], kq[it][1]); kw.y = cvt_pk_bf16(kq[it][2], kq[it][3]);
;       *(u32x2*)(Ks + j * 144 + d4 * 2) = kw;
;       Vt[(d4 + 0) * 152 + j] = f2bf(vq[it][0]); Vt[(d4 + 1) * 152 + j] = f2bf(vq[it][1]);
;       Vt[(d4 + 2) * 152 + j] = f2bf(vq[it][2]); Vt[(d4 + 3) * 152 + j] = f2bf(vq[it][3]);
;       if (j >= 8) { *(f32x4*)(ok + ((j - 8) * 2 + kvh) * 64 + d4) = kq[it]; *(f32x4*)(ov + ((j - 8) * 2 + kvh) * 64 + d4) = vq[it]; }
;     }
;     *(bf16_t*)(Ks + (128 + jn) * 144 + dn * 2) = knb; Vt[dn * 152 + 128 + jn] = vnb;
;     ok[((120 + jn) * 2 + kvh) * 64 + dn] = bf2f(knb); ov[((120 + jn) * 2 + kvh) * 64 + dn] = bf2f(vnb);
;     if (tid < 64) { *(u32x4*)(Ks + (136 + (tid >> 3)) * 144 + (tid & 7) * 16) = (u32x4){0u, 0u, 0u, 0u}; *(u32x4*)(Vt + tid * 152 + 136) = (u32x4){0u, 0u, 0u, 0u}; }
;     if (tid < 256) *(u32x4*)(Qs + (tid >> 3) * 144 + (tid & 7) * 16) = qv;
.LBB0_337:
	s_cmpk_gt_i32 s12, 0x1ff
	s_mov_b64 s[0:1], -1
	s_cbranch_scc0 .LBB0_353
	s_add_i32 s0, s12, 0xfffffe00
	s_lshr_b32 s0, s0, 1
	s_lshl_b32 s1, s0, 3
	s_add_i32 s0, s0, s13
	v_mov_b32_e32 v47, v171
	s_add_i32 s6, s1, 0x4000
	s_ashr_i32 s1, s0, 31
	v_readlane_b32 s44, v248, 20
	s_and_b32 s26, s12, 1
	s_lshl_b64 s[2:3], s[0:1], 16
	v_readlane_b32 s54, v248, 30
	v_ashrrev_i32_e32 v48, 3, v47
	v_readlane_b32 s55, v248, 31
	s_add_u32 s4, s54, s2
	v_and_b32_e32 v4, 0x3fffffe, v48
	v_readlane_b32 s56, v248, 32
	s_addc_u32 s5, s55, s3
	v_lshlrev_b32_e32 v0, 2, v47
	v_or_b32_e32 v4, s26, v4
	v_readlane_b32 s57, v248, 33
	s_add_u32 s2, s56, s2
	v_and_b32_e32 v42, 60, v0
	v_lshlrev_b32_e32 v4, 6, v4
	s_addc_u32 s3, s57, s3
	v_lshlrev_b32_e32 v168, 2, v42
	v_ashrrev_i32_e32 v5, 31, v4
	s_waitcnt lgkmcnt(0)
	v_lshl_add_u64 v[0:1], s[4:5], 0, v[168:169]
	v_lshl_add_u64 v[2:3], s[2:3], 0, v[168:169]
	v_lshlrev_b64 v[4:5], 2, v[4:5]
	v_lshl_add_u64 v[6:7], v[0:1], 0, v[4:5]
	v_lshl_add_u64 v[4:5], v[2:3], 0, v[4:5]
	v_add_u32_e32 v52, 0x200, v47
	v_mov_b64_e32 v[32:33], v[114:115]
	v_mov_b64_e32 v[34:35], v[116:117]
	v_lshrrev_b32_e32 v4, 3, v52
	v_and_b32_e32 v4, 0x3fffffe, v4
	v_or_b32_e32 v4, s26, v4
	v_lshlrev_b32_e32 v4, 6, v4
	v_ashrrev_i32_e32 v5, 31, v4
	v_lshlrev_b64 v[4:5], 2, v[4:5]
	v_mov_b64_e32 v[28:29], v[110:111]
	v_mov_b64_e32 v[30:31], v[112:113]
	v_lshl_add_u64 v[6:7], v[0:1], 0, v[4:5]
	v_lshl_add_u64 v[4:5], v[2:3], 0, v[4:5]
	v_add_u32_e32 v51, 0x400, v47
	v_mov_b64_e32 v[24:25], v[122:123]
	v_mov_b64_e32 v[26:27], v[124:125]
	v_lshrrev_b32_e32 v4, 3, v51
	v_and_b32_e32 v4, 0x3fffffe, v4
	v_or_b32_e32 v4, s26, v4
	v_lshlrev_b32_e32 v4, 6, v4
	v_ashrrev_i32_e32 v5, 31, v4
	v_lshlrev_b64 v[4:5], 2, v[4:5]
	v_mov_b64_e32 v[20:21], v[118:119]
	v_mov_b64_e32 v[22:23], v[120:121]
	v_lshl_add_u64 v[6:7], v[0:1], 0, v[4:5]
	v_lshl_add_u64 v[4:5], v[2:3], 0, v[4:5]
	v_add_u32_e32 v50, 0x600, v47
	v_mov_b64_e32 v[16:17], v[130:131]
	v_mov_b64_e32 v[18:19], v[132:133]
	v_lshrrev_b32_e32 v4, 3, v50
	v_and_b32_e32 v4, 0x3fffffe, v4
	v_or_b32_e32 v4, s26, v4
	v_lshlrev_b32_e32 v4, 6, v4
	v_ashrrev_i32_e32 v5, 31, v4
	v_lshlrev_b64 v[8:9], 2, v[4:5]
	v_lshl_add_u64 v[0:1], v[0:1], 0, v[8:9]
	v_ashrrev_i32_e32 v36, 6, v47
	v_mov_b64_e32 v[12:13], v[126:127]
	v_mov_b64_e32 v[14:15], v[128:129]
	v_ashrrev_i32_e32 v37, 31, v36
	v_mov_b64_e32 v[4:5], v[134:135]
	v_mov_b64_e32 v[6:7], v[136:137]
	v_lshl_add_u64 v[0:1], v[2:3], 0, v[8:9]
	v_mov_b64_e32 v[8:9], v[138:139]
	v_mov_b64_e32 v[10:11], v[140:141]
	v_lshl_add_u64 v[0:1], v[36:37], 0, s[6:7]
	v_mov_b64_e32 v[2:3], s[30:31]
	v_mad_u64_u32 v[2:3], s[2:3], v0, s95, v[2:3]
	v_and_b32_e32 v49, 63, v47
	v_mad_i32_i24 v3, v1, s95, v3
	s_lshl_b32 s2, s26, 7
	s_mov_b32 s3, s7
	v_lshlrev_b32_e32 v40, 1, v49
	v_mov_b32_e32 v41, v169
	v_lshl_add_u64 v[0:1], v[2:3], 0, s[2:3]
	v_lshl_add_u64 v[0:1], v[0:1], 0, v[40:41]
	v_add_co_u32_e32 v0, vcc, 0x1000, v0
	s_movk_i32 s2, 0x100
	s_nop 0
	v_addc_co_u32_e32 v1, vcc, 0, v1, vcc
	v_mov_b32_e32 v41, v142
	v_mov_b32_e32 v37, v143
	v_lshlrev_b32_e32 v1, 4, v47
	v_cmp_gt_i32_e32 vcc, s2, v47
	v_mov_b32_e32 v0, 0
	v_and_b32_e32 v38, 0x70, v1
	v_mov_b32_e32 v1, 0
	v_mov_b32_e32 v2, 0
	v_mov_b32_e32 v3, 0
	v_readlane_b32 s45, v248, 21
	v_readlane_b32 s46, v248, 22
	v_readlane_b32 s47, v248, 23
	v_readlane_b32 s48, v248, 24
	v_readlane_b32 s49, v248, 25
	v_readlane_b32 s50, v248, 26
	v_readlane_b32 s51, v248, 27
	v_readlane_b32 s52, v248, 28
	v_readlane_b32 s53, v248, 29
	v_readlane_b32 s58, v248, 34
	v_readlane_b32 s59, v248, 35
	s_and_saveexec_b64 s[2:3], vcc
	s_cbranch_execz .LBB0_340
	v_lshrrev_b32_e32 v0, 3, v47
	v_and_or_b32 v0, v0, 7, s6
	s_movk_i32 s4, 0x1b00
	v_and_b32_e32 v2, 0xffffffc0, v47
	v_mul_lo_u32 v0, v0, s4
	v_mov_b32_e32 v1, v169
	v_lshl_add_u32 v2, s26, 8, v2
	v_lshl_add_u64 v[0:1], v[0:1], 1, s[30:31]
	v_ashrrev_i32_e32 v3, 31, v2
	v_lshl_add_u64 v[0:1], v[2:3], 1, v[0:1]
	v_mov_b32_e32 v39, v169
	v_lshl_add_u64 v[0:1], v[0:1], 0, v[38:39]
	v_mov_b64_e32 v[0:1], v[144:145]
	v_mov_b64_e32 v[2:3], v[146:147]
.LBB0_340:
	s_or_b64 exec, exec, s[2:3]
	s_lshl_b64 s[0:1], s[0:1], 14
	s_lshl_b32 s27, s26, 6
	s_lshl_b64 s[0:1], s[0:1], 2
	s_add_u32 s2, s14, s0
	s_addc_u32 s3, s15, s1
	s_add_u32 s4, s16, s0
	v_lshl_add_u32 v46, v42, 1, 0
	s_movk_i32 s0, 0x12e
	v_ashrrev_i32_e32 v53, 4, v47
	s_addc_u32 s5, s17, s1
	v_mad_u32_u24 v39, v42, s0, v46
	v_cvt_pk_bf16_f32 v54, v28, v29
	v_cvt_pk_bf16_f32 v55, v30, v31
	v_mad_u64_u32 v[56:57], s[0:1], v53, s33, v[46:47]
	ds_write_b64 v56, v[54:55]
	s_nop 0
	v_cvt_pk_bf16_f32 v54, v32, s0
	v_lshl_add_u32 v55, v53, 1, v39
	ds_write_b16 v55, v54 offset:20736
	v_cvt_pk_bf16_f32 v54, v33, s0
	ds_write_b16 v55, v54 offset:21040
	v_cvt_pk_bf16_f32 v54, v34, s0
	v_lshl_add_u64 v[42:43], s[2:3], 0, v[168:169]
	v_lshl_add_u64 v[44:45], s[4:5], 0, v[168:169]
	ds_write_b16 v55, v54 offset:21344
	v_cvt_pk_bf16_f32 v54, v35, s0
	v_cmp_lt_i32_e64 s[0:1], 7, v53
	ds_write_b16 v55, v54 offset:21648
	s_and_saveexec_b64 s[8:9], s[0:1]
	s_cbranch_execz .LBB0_342
	v_lshl_or_b32 v53, v53, 7, s27
	v_add_u32_e32 v168, 0xfffffc00, v53
	v_lshlrev_b64 v[54:55], 2, v[168:169]
	v_lshl_add_u64 v[56:57], v[42:43], 0, v[54:55]
	v_lshl_add_u64 v[54:55], v[44:45], 0, v[54:55]
	global_store_dwordx4 v[56:57], v[28:31], off
	global_store_dwordx4 v[54:55], v[32:35], off

; DEV float bf2f(unsigned h) { return __uint_as_float(h << 16); }
; DEV float log_gamma(int h) { return log1pf(-exp2f(-5.0f - (float)h)); }
; DEV void ret_sample_item(const Params& p, int l, int item, unsigned char* smem) {
;     ...
;   const size_t rowbase = (size_t)TP + b * 8;
;   const float lg = log_gamma(h);
;   {
;     const int i = tid >> 6, d = tid & 63;
;     qs[tid] = bf2f(Z[(rowbase + i) * NIN + RQ + h * 64 + d]);
;     ks[tid] = bf2f(Z[(rowbase + i) * NIN + RK + h * 64 + d]) * 0.125f;
; #pragma unroll
;     for (int it = 0; it < 2; ++it) { const int idx = tid + it * 512, ii = idx >> 7, e = idx & 127; vs[idx] = bf2f(Z[(rowbase + ii) * NIN + RV + h * 128 + e]); }
;   }
.Lrs_skip_s0:
	s_and_b32 s2, s12, 3
	v_cvt_f32_ubyte0_e32 v0, s2
	v_sub_f32_e32 v0, 0xc0a00000, v0
	s_mov_b32 s3, 0xc2fc0000
	s_lshl_b32 s0, s12, 1
	v_cmp_gt_f32_e32 vcc, s3, v0
	s_and_b32 s0, s0, -8
	s_ashr_i32 s1, s0, 31
	v_cndmask_b32_e32 v2, 0, v203, vcc
	v_add_f32_e32 v0, v0, v2
	s_add_u32 s0, s0, 0x4000
	v_exp_f32_e32 v0, v0
	s_addc_u32 s1, s1, 0
	s_and_b64 s[4:5], vcc, exec
	s_cselect_b32 s3, 0xffffffc0, 0
	v_ldexp_f32 v10, v0, s3
	v_sub_f32_e32 v0, 1.0, v10
	v_add_f32_e32 v2, -1.0, v0
	v_sub_f32_e32 v3, v2, v0
	v_add_f32_e32 v3, 1.0, v3
	v_sub_f32_e64 v2, -v10, v2
	v_add_f32_e32 v4, v2, v3
	v_frexp_mant_f32_e32 v5, v0
	v_cvt_f64_f32_e32 v[2:3], v0
	s_mov_b32 s3, 0x3f2aaaab
	v_frexp_exp_i32_f64_e32 v2, v[2:3]
	v_cmp_gt_f32_e32 vcc, s3, v5
	s_waitcnt lgkmcnt(0)
	v_mov_b32_e32 v1, v171
	s_lshl_b32 s6, s2, 7
	v_subbrev_co_u32_e32 v11, vcc, 0, v2, vcc
	v_sub_u32_e32 v2, 0, v11
	v_ldexp_f32 v0, v0, v2
	v_add_f32_e32 v3, -1.0, v0
	v_add_f32_e32 v5, 1.0, v0
	v_ldexp_f32 v2, v4, v2
	v_add_f32_e32 v4, 1.0, v3
	v_add_f32_e32 v6, -1.0, v5
	v_sub_f32_e32 v4, v0, v4
	v_sub_f32_e32 v0, v0, v6
	v_add_f32_e32 v4, v2, v4
	v_add_f32_e32 v0, v2, v0
	v_ashrrev_i32_e32 v66, 6, v1
	v_add_f32_e32 v12, v3, v4
	v_add_f32_e32 v13, v5, v0
	v_sub_f32_e32 v3, v12, v3
	v_sub_f32_e32 v2, v13, v5
	v_ashrrev_i32_e32 v67, 31, v66
	v_sub_f32_e32 v15, v4, v3
	v_sub_f32_e32 v16, v0, v2
	v_lshl_add_u64 v[2:3], s[0:1], 0, v[66:67]
	v_mov_b64_e32 v[4:5], s[30:31]
	v_mad_u64_u32 v[64:65], s[4:5], v2, s95, v[4:5]
	v_and_b32_e32 v72, 63, v1
	v_mad_i32_i24 v65, v3, s95, v65
	v_add_u32_e32 v8, 0x200, v1
	v_lshl_add_u64 v[2:3], v[64:65], 0, s[6:7]
	v_lshlrev_b32_e32 v168, 1, v72
	v_ashrrev_i32_e32 v68, 7, v1
	v_ashrrev_i32_e32 v8, 7, v8
	v_lshl_add_u64 v[2:3], v[2:3], 0, v[168:169]
	v_ashrrev_i32_e32 v69, 31, v68
	v_ashrrev_i32_e32 v9, 31, v8
	s_cmp_eq_u32 s12, s74
	s_cbranch_scc1 .Lrs_z1
	global_load_ushort v18, v[2:3], off
	global_load_ushort v19, v[2:3], off offset:512
	s_branch .Lrs_z1d
.Lrs_z1:
	v_mov_b32_e32 v18, v240
	v_mov_b32_e32 v19, v241
.Lrs_z1d:
	v_lshl_add_u64 v[2:3], s[0:1], 0, v[68:69]
	v_lshl_add_u64 v[8:9], s[0:1], 0, v[8:9]
	v_mad_u64_u32 v[6:7], s[4:5], v2, s95, v[4:5]
	v_mad_u64_u32 v[4:5], s[0:1], v8, s95, v[4:5]
	v_and_b32_e32 v0, 0x7f, v1
	v_mad_i32_i24 v7, v3, s95, v7
	s_lshl_b32 s4, s2, 8
	s_mov_b32 s5, s7
	v_mad_i32_i24 v5, v9, s95, v5
	v_lshl_add_u64 v[2:3], v[6:7], 0, s[4:5]
	v_lshlrev_b32_e32 v6, 1, v0
	v_mov_b32_e32 v7, v169
	v_lshl_add_u64 v[4:5], v[4:5], 0, s[4:5]
	v_lshl_add_u64 v[2:3], v[2:3], 0, v[6:7]
	v_lshl_add_u64 v[4:5], v[4:5], 0, v[6:7]
	s_cmp_eq_u32 s12, s74
	s_cbranch_scc1 .Lrs_z2
	global_load_ushort v3, v[2:3], off offset:1024
	s_nop 0
	global_load_ushort v4, v[4:5], off offset:1024
	s_branch .Lrs_z2d
.Lrs_z2:
	v_mov_b32_e32 v3, v242
	v_mov_b32_e32 v4, v243
; DEV float bf2f(unsigned h) { return __uint_as_float(h << 16); }
; DEV float log_gamma(int h) { return log1pf(-exp2f(-5.0f - (float)h)); }
; DEV void ret_sample_item(const Params& p, int l, int item, unsigned char* smem) {
;     ...
;   const float lg = log_gamma(h);
;   {
;     const int i = tid >> 6, d = tid & 63;
;     qs[tid] = bf2f(Z[(rowbase + i) * NIN + RQ + h * 64 + d]);
;     ks[tid] = bf2f(Z[(rowbase + i) * NIN + RK + h * 64 + d]) * 0.125f;
; #pragma unroll
;     for (int it = 0; it < 2; ++it) { const int idx = tid + it * 512, ii = idx >> 7, e = idx & 127; vs[idx] = bf2f(Z[(rowbase + ii) * NIN + RV + h * 128 + e]); }
;   }
;   __syncthreads();
;   if (tid < 64) {
;     const int i = tid >> 3, j = tid & 7;
;     float dsum = 0.f;
;     for (int d = 0; d < 64; ++d) dsum += qs[i * 64 + d] * ks[j * 64 + d];
;     inn[tid] = (i >= j) ? dsum * __expf(lg * (float)(i - j)) : 0.f;
;   }
.Lrs_z2d:
	v_rcp_f32_e32 v14, v13
	s_mov_b32 s0, 0x3f317218
	v_cmp_nlt_f32_e32 vcc, 1.0, v10
	v_mul_f32_e32 v17, v12, v14
	v_mul_f32_e32 v2, v13, v17
	v_fma_f32 v5, v17, v13, -v2
	v_fmac_f32_e32 v5, v17, v16
	v_add_f32_e32 v6, v2, v5
	v_sub_f32_e32 v7, v12, v6
	v_sub_f32_e32 v8, v12, v7
	v_sub_f32_e32 v2, v6, v2
	v_sub_f32_e32 v6, v8, v6
	v_add_f32_e32 v6, v15, v6
	v_sub_f32_e32 v2, v2, v5
	v_add_f32_e32 v2, v2, v6
	v_add_f32_e32 v5, v7, v2
	v_mul_f32_e32 v6, v14, v5
	v_mul_f32_e32 v8, v13, v6
	v_fma_f32 v9, v6, v13, -v8
	v_fmac_f32_e32 v9, v6, v16
	v_sub_f32_e32 v7, v7, v5
	v_add_f32_e32 v2, v2, v7
	v_add_f32_e32 v7, v8, v9
	v_sub_f32_e32 v12, v5, v7
	v_sub_f32_e32 v5, v5, v12
	v_sub_f32_e32 v8, v7, v8
	v_sub_f32_e32 v5, v5, v7
	v_add_f32_e32 v2, v2, v5
	v_sub_f32_e32 v5, v8, v9
	v_add_f32_e32 v2, v5, v2
	v_add_f32_e32 v5, v17, v6
	v_sub_f32_e32 v7, v5, v17
	v_sub_f32_e32 v6, v6, v7
	v_cvt_f32_i32_e32 v7, v11
	v_add_f32_e32 v2, v12, v2
	v_mul_f32_e32 v2, v14, v2
	v_add_f32_e32 v2, v6, v2
	v_mul_f32_e32 v11, 0x3f317218, v7
	v_add_f32_e32 v6, v5, v2
	v_fma_f32 v12, v7, s0, -v11
	v_mul_f32_e32 v8, v6, v6
	v_fmac_f32_e32 v12, 0xb102e308, v7
	v_sub_f32_e32 v5, v6, v5
	v_fmamk_f32 v9, v8, 0x3e9b6dac, v201
	v_sub_f32_e32 v2, v2, v5
	v_add_f32_e32 v5, v11, v12
	v_fmaak_f32 v9, v8, v9, 0x3f2aaada
	v_sub_f32_e32 v7, v5, v11
	v_ldexp_f32 v11, v6, 1
	v_mul_f32_e32 v6, v6, v8
	v_mul_f32_e32 v6, v6, v9
	v_add_f32_e32 v8, v11, v6
	v_sub_f32_e32 v9, v8, v11
	v_ldexp_f32 v2, v2, 1
	v_sub_f32_e32 v6, v6, v9
	v_add_f32_e32 v2, v2, v6
	v_add_f32_e32 v6, v8, v2
	v_sub_f32_e32 v8, v6, v8
	v_sub_f32_e32 v2, v2, v8
	v_add_f32_e32 v8, v5, v6
	v_sub_f32_e32 v9, v8, v5
	v_sub_f32_e32 v11, v8, v9
	v_sub_f32_e32 v7, v12, v7
	v_sub_f32_e32 v5, v5, v11
	v_sub_f32_e32 v6, v6, v9
	v_add_f32_e32 v5, v6, v5
	v_add_f32_e32 v6, v7, v2
	v_sub_f32_e32 v9, v6, v7
	v_sub_f32_e32 v11, v6, v9
	v_add_f32_e32 v5, v6, v5
	v_sub_f32_e32 v7, v7, v11
	v_sub_f32_e32 v2, v2, v9
	v_add_f32_e32 v6, v8, v5
	v_add_f32_e32 v2, v2, v7
	v_sub_f32_e32 v7, v6, v8
	v_sub_f32_e32 v5, v5, v7
	v_add_f32_e32 v5, v2, v5
	v_lshl_add_u32 v2, v1, 2, 0
	s_waitcnt vmcnt(0)
	v_lshlrev_b32_e32 v3, 16, v3
	v_lshlrev_b32_e32 v4, 16, v4
	ds_write2st64_b32 v2, v3, v4 offset0:16 offset1:24
	v_add_f32_e32 v3, v6, v5
	v_cndmask_b32_e32 v3, v204, v3, vcc
	v_cmp_neq_f32_e32 vcc, 1.0, v10
	s_mov_b32 s0, 0x33800000
	v_lshlrev_b32_e32 v8, 16, v19
	v_cndmask_b32_e32 v3, v205, v3, vcc
	v_cmp_gt_f32_e32 vcc, s0, v10
	v_lshlrev_b32_e32 v7, 16, v18
	v_mul_f32_e32 v8, 0x3e000000, v8
	v_cndmask_b32_e64 v67, v3, -v10, vcc
	v_cmp_gt_i32_e32 vcc, 64, v1
	ds_write2st64_b32 v2, v7, v8 offset1:8
	s_waitcnt lgkmcnt(0)
	s_barrier
	s_and_saveexec_b64 s[0:1], vcc
	s_cbranch_execz .LBB0_356
	v_ashrrev_i32_e32 v3, 3, v1
	v_and_b32_e32 v1, 7, v1
	v_lshl_add_u32 v36, v3, 8, 0
	v_lshl_add_u32 v37, v1, 8, 0
	ds_read_b128 v[4:7], v36
	ds_read_b128 v[8:11], v36 offset:16
	ds_read_b128 v[12:15], v37 offset:2048
	ds_read_b128 v[16:19], v36 offset:32
	ds_read_b128 v[20:23], v36 offset:48
	ds_read_b128 v[24:27], v37 offset:2064
	ds_read_b128 v[28:31], v37 offset:2080
	ds_read_b128 v[32:35], v37 offset:2096
	s_waitcnt lgkmcnt(5)
	v_fma_f32 v38, v4, v12, 0
	v_fmac_f32_e32 v38, v5, v13
	v_fmac_f32_e32 v38, v6, v14
	v_fmac_f32_e32 v38, v7, v15
	s_waitcnt lgkmcnt(2)
	v_fmac_f32_e32 v38, v8, v24
	v_fmac_f32_e32 v38, v9, v25
	v_fmac_f32_e32 v38, v10, v26
	v_fmac_f32_e32 v38, v11, v27
	s_waitcnt lgkmcnt(1)
	v_fmac_f32_e32 v38, v16, v28
	v_fmac_f32_e32 v38, v17, v29
	v_fmac_f32_e32 v38, v18, v30
	v_fmac_f32_e32 v38, v19, v31
	ds_read_b128 v[4:7], v36 offset:64
	ds_read_b128 v[8:11], v37 offset:2112
	s_waitcnt lgkmcnt(2)
	v_fmac_f32_e32 v38, v20, v32
	v_fmac_f32_e32 v38, v21, v33
	v_fmac_f32_e32 v38, v22, v34
	v_fmac_f32_e32 v38, v23, v35
	ds_read_b128 v[12:15], v36 offset:80
	ds_read_b128 v[16:19], v37 offset:2128
	s_waitcnt lgkmcnt(2)
	v_fmac_f32_e32 v38, v4, v8
	v_fmac_f32_e32 v38, v5, v9
	v_fmac_f32_e32 v38, v6, v10
	v_fmac_f32_e32 v38, v7, v11
	ds_read_b128 v[4:7], v36 offset:96
	ds_read_b128 v[8:11], v37 offset:2144
	s_waitcnt lgkmcnt(2)
	v_fmac_f32_e32 v38, v12, v16
	v_fmac_f32_e32 v38, v13, v17
	v_fmac_f32_e32 v38, v14, v18
	v_fmac_f32_e32 v38, v15, v19
	ds_read_b128 v[12:15], v36 offset:112
	ds_read_b128 v[16:19], v37 offset:2160
	s_waitcnt lgkmcnt(2)
	v_fmac_f32_e32 v38, v4, v8
	v_fmac_f32_e32 v38, v5, v9
	v_fmac_f32_e32 v38, v6, v10
	v_fmac_f32_e32 v38, v7, v11
	ds_read_b128 v[4:7], v36 offset:128
	ds_read_b128 v[8:11], v37 offset:2176
	s_waitcnt lgkmcnt(2)
	v_fmac_f32_e32 v38, v12, v16
	v_fmac_f32_e32 v38, v13, v17
	v_fmac_f32_e32 v38, v14, v18
	v_fmac_f32_e32 v38, v15, v19
	ds_read_b128 v[12:15], v36 offset:144
	ds_read_b128 v[16:19], v37 offset:2192
	s_waitcnt lgkmcnt(2)
	v_fmac_f32_e32 v38, v4, v8
	v_fmac_f32_e32 v38, v5, v9
	v_fmac_f32_e32 v38, v6, v10
	v_fmac_f32_e32 v38, v7, v11
	ds_read_b128 v[4:7], v36 offset:160
	ds_read_b128 v[8:11], v37 offset:2208
	s_waitcnt lgkmcnt(2)
	v_fmac_f32_e32 v38, v12, v16
	v_fmac_f32_e32 v38, v13, v17
	v_fmac_f32_e32 v38, v14, v18
	v_fmac_f32_e32 v38, v15, v19
	ds_read_b128 v[12:15], v36 offset:176
	ds_read_b128 v[16:19], v37 offset:2224
	s_waitcnt lgkmcnt(2)
	v_fmac_f32_e32 v38, v4, v8
	v_fmac_f32_e32 v38, v5, v9
	v_fmac_f32_e32 v38, v6, v10
	v_fmac_f32_e32 v38, v7, v11
	ds_read_b128 v[4:7], v36 offset:192
	ds_read_b128 v[8:11], v37 offset:2240
	s_waitcnt lgkmcnt(2)
	v_fmac_f32_e32 v38, v12, v16
	v_fmac_f32_e32 v38, v13, v17
	v_fmac_f32_e32 v38, v14, v18
	v_fmac_f32_e32 v38, v15, v19
	ds_read_b128 v[12:15], v36 offset:208
	ds_read_b128 v[16:19], v37 offset:2256
	s_waitcnt lgkmcnt(2)
	v_fmac_f32_e32 v38, v4, v8
	v_fmac_f32_e32 v38, v5, v9
	v_fmac_f32_e32 v38, v6, v10
	v_fmac_f32_e32 v38, v7, v11
	ds_read_b128 v[4:7], v36 offset:224
	ds_read_b128 v[8:11], v37 offset:2272
	s_waitcnt lgkmcnt(2)
	v_fmac_f32_e32 v38, v12, v16
	v_fmac_f32_e32 v38, v13, v17
	v_pk_mul_f32 v[12:13], v[14:15], v[18:19]
	v_cmp_ge_i32_e32 vcc, v3, v1
	v_add_f32_e32 v12, v38, v12
	v_add_f32_e32 v20, v12, v13
	s_waitcnt lgkmcnt(0)
	v_pk_mul_f32 v[4:5], v[4:5], v[8:9]
	ds_read_b128 v[12:15], v36 offset:240
	ds_read_b128 v[16:19], v37 offset:2288
	v_add_f32_e32 v4, v20, v4
	v_add_f32_e32 v8, v4, v5
	v_pk_mul_f32 v[4:5], v[6:7], v[10:11]
	s_nop 0
	v_add_f32_e32 v4, v8, v4
	v_add_f32_e32 v6, v4, v5
	v_sub_u32_e32 v4, v3, v1
	v_cvt_f32_i32_e32 v7, v4
	s_waitcnt lgkmcnt(0)
	v_pk_mul_f32 v[4:5], v[12:13], v[16:17]
	s_nop 0
	v_add_f32_e32 v4, v6, v4
	v_add_f32_e32 v6, v4, v5
	v_mul_f32_e32 v4, v67, v7
	v_mul_f32_e32 v4, 0x3fb8aa3b, v4
	v_exp_f32_e32 v7, v4
	v_pk_mul_f32 v[4:5], v[14:15], v[18:19]
	s_nop 0
	v_add_f32_e32 v4, v6, v4
	v_add_f32_e32 v4, v4, v5
	v_mul_f32_e32 v4, v7, v4
	v_cndmask_b32_e32 v1, 0, v4, vcc
	ds_write_b32 v2, v1 offset:8192

; DEV float bf2f(unsigned h) { return __uint_as_float(h << 16); }
; DEV void conv_and_window(const Params& p, int l) {
;     ...
;   for (int c = gtid; c < 4 * 128 * 128 * 2; c += gstride) {
;     const int col = c & 127, j = (c >> 7) & 127, b = (c >> 14) & 3, kv = c >> 16;
;     const float v = bf2f(Z[((size_t)b * SEQ + SEQ - 128 + j) * NIN + (kv ? AV : AK) + col]);
;     p.out[(kv ? O_WVP : O_WKP) + (size_t)((l * 4 + b) * 128 + j) * 128 + col] = v;
;   }
.LBB0_420:
	v_bfe_u32 v3, v44, 7, 7
	v_bfe_u32 v4, v44, 14, 2
	v_lshl_or_b32 v0, v4, 12, v3
	v_cmp_gt_u32_e64 s[0:1], s8, v44
	v_mul_u32_u24_e32 v5, 0x1b00, v0
	v_add_u32_e32 v44, s6, v44
	v_cndmask_b32_e64 v168, v210, v211, s[0:1]
	v_lshl_add_u64 v[0:1], s[30:31], 0, v[168:169]
	v_lshlrev_b32_e32 v168, 1, v5
	v_lshl_add_u64 v[0:1], v[0:1], 0, v[168:169]
	v_lshlrev_b32_e32 v168, 1, v2
	v_lshl_add_u64 v[0:1], v[0:1], 0, v[168:169]
	v_add_co_u32_e32 v0, vcc, s26, v0
	v_cndmask_b32_e64 v168, v214, v215, s[0:1]
	s_nop 0
	v_addc_co_u32_e32 v1, vcc, 0, v1, vcc
	v_mov_b32_e32 v0, v246
	v_cmp_lt_i32_e32 vcc, s40, v44
	s_or_b64 s[4:5], vcc, s[4:5]
	v_lshlrev_b32_e32 v6, 16, v0
	v_lshlrev_b32_e32 v0, 7, v4
	v_or3_b32 v0, v0, s12, v3
	v_ashrrev_i32_e32 v1, 31, v0
	v_lshl_add_u64 v[4:5], s[22:23], 0, v[168:169]
	v_lshlrev_b64 v[0:1], 9, v[0:1]
	v_lshl_add_u64 v[0:1], v[4:5], 0, v[0:1]
	v_lshlrev_b32_e32 v168, 2, v2
	v_lshl_add_u64 v[0:1], v[0:1], 0, v[168:169]
	global_store_dword v[0:1], v6, off
	s_andn2_b64 exec, exec, s[4:5]
	s_cbranch_execnz .LBB0_420
